# in-proj K-loop: LDS fragment address adds hoisted to loop-invariant VGPRs as in gate|up
# baseline (speedup 1.0000x reference)
.LBB0_144:
	s_ashr_i32 s19, s18, 31
	v_cmp_lt_i64_e32 vcc, s[10:11], v[140:141]
	s_lshl_b64 s[10:11], s[18:19], 19
	s_add_u32 s22, s86, s10
	s_addc_u32 s23, s87, s11
	s_and_b64 s[10:11], vcc, exec
	s_cselect_b32 s9, s23, s3
	s_cselect_b32 s12, s22, s2
	s_cmp_eq_u32 s16, 5
	s_cselect_b32 s17, 7, s16
	s_cmp_eq_u32 s16, 7
	s_cselect_b32 s16, 5, s17
	s_ashr_i32 s17, s16, 31
	s_lshl_b64 s[10:11], s[16:17], 19
	s_add_u32 s24, s41, s10
	s_addc_u32 s25, s14, s11
	s_and_b64 s[10:11], vcc, exec
	s_cselect_b32 s13, s25, s7
	s_cselect_b32 s17, s24, s6
	s_add_u32 s2, s2, 0x40080
	s_addc_u32 s3, s3, 0
	s_add_u32 s19, s6, 0x100
	v_mov_b32_e32 v0, 0
	s_addc_u32 s27, s7, 0
	s_waitcnt lgkmcnt(0)
	s_mov_b32 s28, -2
	v_mov_b32_e32 v1, v0
	v_mov_b64_e32 v[2:3], 0
	v_mov_b64_e32 v[4:5], 0
	v_mov_b64_e32 v[6:7], 0
	v_mov_b64_e32 v[8:9], 0
	v_mov_b64_e32 v[10:11], 0
	v_mov_b64_e32 v[12:13], 0
	v_mov_b64_e32 v[14:15], 0
	v_mov_b64_e32 v[16:17], 0
	v_mov_b64_e32 v[18:19], 0
	v_mov_b64_e32 v[20:21], 0
	v_mov_b64_e32 v[22:23], 0
	v_mov_b64_e32 v[24:25], 0
	v_mov_b64_e32 v[26:27], 0
	v_mov_b64_e32 v[28:29], 0
	v_mov_b64_e32 v[30:31], 0
	v_mov_b64_e32 v[32:33], 0
	v_mov_b64_e32 v[34:35], 0
	v_mov_b64_e32 v[36:37], 0
	v_mov_b64_e32 v[38:39], 0
	v_mov_b64_e32 v[40:41], 0
	v_mov_b64_e32 v[42:43], 0
	v_mov_b64_e32 v[44:45], 0
	v_mov_b64_e32 v[46:47], 0
	v_mov_b64_e32 v[48:49], 0
	v_mov_b64_e32 v[50:51], 0
	v_mov_b64_e32 v[52:53], 0
	v_mov_b64_e32 v[54:55], 0
	v_mov_b64_e32 v[56:57], 0
	v_mov_b64_e32 v[58:59], 0
	v_mov_b64_e32 v[60:61], 0
	v_mov_b64_e32 v[62:63], 0
	v_mov_b64_e32 v[64:65], 0
	v_mov_b64_e32 v[66:67], 0
	v_mov_b64_e32 v[68:69], 0
	v_mov_b64_e32 v[70:71], 0
	v_mov_b64_e32 v[72:73], 0
	v_mov_b64_e32 v[74:75], 0
	v_mov_b64_e32 v[76:77], 0
	v_mov_b64_e32 v[78:79], 0
	v_mov_b64_e32 v[80:81], 0
	v_mov_b64_e32 v[82:83], 0
	v_mov_b64_e32 v[84:85], 0
	v_mov_b64_e32 v[86:87], 0
	v_mov_b64_e32 v[88:89], 0
	v_mov_b64_e32 v[90:91], 0
	v_mov_b64_e32 v[92:93], 0
	v_mov_b64_e32 v[94:95], 0
	v_mov_b64_e32 v[96:97], 0
	v_mov_b64_e32 v[98:99], 0
	v_mov_b64_e32 v[100:101], 0
	v_mov_b64_e32 v[102:103], 0
	v_mov_b64_e32 v[104:105], 0
	v_mov_b64_e32 v[106:107], 0
	v_mov_b64_e32 v[108:109], 0
	v_mov_b64_e32 v[110:111], 0
	v_mov_b64_e32 v[112:113], 0
	v_mov_b64_e32 v[114:115], 0
	v_mov_b64_e32 v[116:117], 0
	v_mov_b64_e32 v[118:119], 0
	v_mov_b64_e32 v[120:121], 0
	v_mov_b64_e32 v[122:123], 0
	v_mov_b64_e32 v[124:125], 0
	v_mov_b64_e32 v[126:127], 0
	v_add_u32_e32 v200, 0x14000, v215
	v_add_u32_e32 v201, 0x18000, v215
	v_add_u32_e32 v202, 0x1c000, v215
	v_add_u32_e32 v246, 0x10000, v215
	v_add_u32_e32 v166, 0x10000, v215
	ds_read_b128 v[128:131], v166
	ds_read_b128 v[158:161], v166 offset:1024
	ds_read_b128 v[162:165], v166 offset:2048
	ds_read_b128 v[166:169], v166 offset:3072
.LBB0_145:
	s_add_u32 s6, s2, 0xfffc0080
	s_addc_u32 s7, s3, -1
	s_add_i32 s29, 0, 0x10000
	s_cmp_eq_u32 s28, 12
	s_cselect_b32 s11, s9, s7
	s_cselect_b32 s10, s12, s6
	s_cselect_b32 s7, s13, s27
	s_cselect_b32 s6, s17, s19
	s_add_i32 m0, s50, 0xc000
	ds_read_b128 v[170:173], v216
	ds_read_b128 v[178:181], v216 offset:2048
	ds_read_b128 v[186:189], v216 offset:4096
	ds_read_b128 v[222:225], v216 offset:6144
	ds_read_b128 v[174:177], v216 offset:1024
	ds_read_b128 v[182:185], v216 offset:3072
	ds_read_b128 v[218:221], v216 offset:5120
	ds_read_b128 v[226:229], v216 offset:7168
	global_load_lds_dwordx4 v154, s[2:3]
	s_add_i32 m0, s50, 0xe000
	s_nop 0
	global_load_lds_dwordx4 v156, s[2:3]
	s_waitcnt lgkmcnt(8)
	s_waitcnt vmcnt(10)
	s_barrier
	s_waitcnt lgkmcnt(4)
	v_mfma_f32_16x16x32_bf16 v[124:127], v[128:131], v[170:173], v[124:127]
	v_mfma_f32_16x16x32_bf16 v[120:123], v[162:165], v[170:173], v[120:123]
	v_mfma_f32_16x16x32_bf16 v[108:111], v[128:131], v[178:181], v[108:111]
	v_mfma_f32_16x16x32_bf16 v[104:107], v[162:165], v[178:181], v[104:107]
	v_mfma_f32_16x16x32_bf16 v[92:95], v[128:131], v[186:189], v[92:95]
	v_mfma_f32_16x16x32_bf16 v[88:91], v[162:165], v[186:189], v[88:91]
	v_mfma_f32_16x16x32_bf16 v[76:79], v[128:131], v[222:225], v[76:79]
	v_mfma_f32_16x16x32_bf16 v[72:75], v[162:165], v[222:225], v[72:75]
	s_waitcnt lgkmcnt(0)
	v_mfma_f32_16x16x32_bf16 v[124:127], v[158:161], v[174:177], v[124:127]
	v_mfma_f32_16x16x32_bf16 v[120:123], v[166:169], v[174:177], v[120:123]
	v_mfma_f32_16x16x32_bf16 v[108:111], v[158:161], v[182:185], v[108:111]
	v_mfma_f32_16x16x32_bf16 v[104:107], v[166:169], v[182:185], v[104:107]
	v_mfma_f32_16x16x32_bf16 v[92:95], v[158:161], v[218:221], v[92:95]
	v_mfma_f32_16x16x32_bf16 v[88:91], v[166:169], v[218:221], v[88:91]
	v_mfma_f32_16x16x32_bf16 v[76:79], v[158:161], v[226:229], v[76:79]
	v_mfma_f32_16x16x32_bf16 v[72:75], v[166:169], v[226:229], v[72:75]
	s_barrier
	s_add_i32 s34, 0, 0x14000
	s_add_i32 s29, s29, s15
	s_mov_b32 m0, s29
	ds_read_b128 v[230:233], v200
	ds_read_b128 v[238:241], v200 offset:2048
	ds_read_b128 v[234:237], v200 offset:1024
	ds_read_b128 v[242:245], v200 offset:3072
	global_load_lds_dwordx4 v150, s[6:7]
	s_add_i32 m0, s29, 0x2000
	s_nop 0
	global_load_lds_dwordx4 v152, s[6:7]
	s_waitcnt vmcnt(10)
	s_barrier
	s_waitcnt lgkmcnt(2)
	v_mfma_f32_16x16x32_bf16 v[116:119], v[230:233], v[170:173], v[116:119]
	v_mfma_f32_16x16x32_bf16 v[112:115], v[238:241], v[170:173], v[112:115]
	v_mfma_f32_16x16x32_bf16 v[100:103], v[230:233], v[178:181], v[100:103]
	v_mfma_f32_16x16x32_bf16 v[96:99], v[238:241], v[178:181], v[96:99]
	v_mfma_f32_16x16x32_bf16 v[84:87], v[230:233], v[186:189], v[84:87]
	v_mfma_f32_16x16x32_bf16 v[80:83], v[238:241], v[186:189], v[80:83]
	v_mfma_f32_16x16x32_bf16 v[68:71], v[230:233], v[222:225], v[68:71]
	v_mfma_f32_16x16x32_bf16 v[64:67], v[238:241], v[222:225], v[64:67]
	s_waitcnt lgkmcnt(0)
	v_mfma_f32_16x16x32_bf16 v[116:119], v[234:237], v[174:177], v[116:119]
	v_mfma_f32_16x16x32_bf16 v[112:115], v[242:245], v[174:177], v[112:115]
	v_mfma_f32_16x16x32_bf16 v[100:103], v[234:237], v[182:185], v[100:103]
	v_mfma_f32_16x16x32_bf16 v[96:99], v[242:245], v[182:185], v[96:99]
	v_mfma_f32_16x16x32_bf16 v[84:87], v[234:237], v[218:221], v[84:87]
	v_mfma_f32_16x16x32_bf16 v[80:83], v[242:245], v[218:221], v[80:83]
	v_mfma_f32_16x16x32_bf16 v[68:71], v[234:237], v[226:229], v[68:71]
	v_mfma_f32_16x16x32_bf16 v[64:67], v[242:245], v[226:229], v[64:67]
	s_mov_b32 m0, s50
	v_lshl_add_u64 v[248:249], s[10:11], 0, v[150:151]
	s_barrier
	ds_read_b128 v[170:173], v216 offset:16384
	ds_read_b128 v[178:181], v216 offset:18432
	ds_read_b128 v[186:189], v216 offset:20480
	ds_read_b128 v[222:225], v216 offset:22528
	ds_read_b128 v[174:177], v216 offset:17408
	ds_read_b128 v[182:185], v216 offset:19456
	ds_read_b128 v[218:221], v216 offset:21504
	ds_read_b128 v[226:229], v216 offset:23552
	global_load_lds_dwordx4 v150, s[10:11]
	v_lshl_add_u64 v[250:251], s[10:11], 0, v[152:153]
	s_mov_b32 m0, s51
	s_nop 0
	global_load_lds_dwordx4 v152, s[10:11]
	s_waitcnt vmcnt(10)
	s_barrier
	s_waitcnt lgkmcnt(4)
	v_mfma_f32_16x16x32_bf16 v[60:63], v[128:131], v[170:173], v[60:63]
	v_mfma_f32_16x16x32_bf16 v[56:59], v[162:165], v[170:173], v[56:59]
	v_mfma_f32_16x16x32_bf16 v[44:47], v[128:131], v[178:181], v[44:47]
	v_mfma_f32_16x16x32_bf16 v[40:43], v[162:165], v[178:181], v[40:43]
	v_mfma_f32_16x16x32_bf16 v[28:31], v[128:131], v[186:189], v[28:31]
	v_mfma_f32_16x16x32_bf16 v[24:27], v[162:165], v[186:189], v[24:27]
	v_mfma_f32_16x16x32_bf16 v[12:15], v[128:131], v[222:225], v[12:15]
	v_mfma_f32_16x16x32_bf16 v[8:11], v[162:165], v[222:225], v[8:11]
	s_waitcnt lgkmcnt(0)
	v_mfma_f32_16x16x32_bf16 v[60:63], v[158:161], v[174:177], v[60:63]
	v_mfma_f32_16x16x32_bf16 v[56:59], v[166:169], v[174:177], v[56:59]
	v_mfma_f32_16x16x32_bf16 v[44:47], v[158:161], v[182:185], v[44:47]
	v_mfma_f32_16x16x32_bf16 v[40:43], v[166:169], v[182:185], v[40:43]
	v_mfma_f32_16x16x32_bf16 v[28:31], v[158:161], v[218:221], v[28:31]
	v_mfma_f32_16x16x32_bf16 v[24:27], v[166:169], v[218:221], v[24:27]
	v_mfma_f32_16x16x32_bf16 v[12:15], v[158:161], v[226:229], v[12:15]
	v_mfma_f32_16x16x32_bf16 v[8:11], v[166:169], v[226:229], v[8:11]
	s_barrier
	s_add_u32 s30, s6, 0x40000
	s_addc_u32 s31, s7, 0
	s_add_i32 s29, s34, s15
	s_mov_b32 m0, s29
	s_nop 0
	global_load_lds_dwordx4 v150, s[30:31]
	s_add_i32 m0, s29, 0x2000
	s_nop 0
	global_load_lds_dwordx4 v152, s[30:31]
	ds_read_b128 v[128:131], v201
	ds_read_b128 v[158:161], v201 offset:1024
	ds_read_b128 v[162:165], v201 offset:2048
	ds_read_b128 v[166:169], v201 offset:3072
	s_waitcnt vmcnt(10)
	s_barrier
	v_mfma_f32_16x16x32_bf16 v[52:55], v[230:233], v[170:173], v[52:55]
	v_mfma_f32_16x16x32_bf16 v[48:51], v[238:241], v[170:173], v[48:51]
	v_mfma_f32_16x16x32_bf16 v[36:39], v[230:233], v[178:181], v[36:39]
	v_mfma_f32_16x16x32_bf16 v[32:35], v[238:241], v[178:181], v[32:35]
	v_mfma_f32_16x16x32_bf16 v[20:23], v[230:233], v[186:189], v[20:23]
	v_mfma_f32_16x16x32_bf16 v[16:19], v[238:241], v[186:189], v[16:19]
	v_mfma_f32_16x16x32_bf16 v[4:7], v[230:233], v[222:225], v[4:7]
	v_mfma_f32_16x16x32_bf16 v[0:3], v[238:241], v[222:225], v[0:3]
	v_mfma_f32_16x16x32_bf16 v[52:55], v[234:237], v[174:177], v[52:55]
	v_mfma_f32_16x16x32_bf16 v[48:51], v[242:245], v[174:177], v[48:51]
	v_mfma_f32_16x16x32_bf16 v[36:39], v[234:237], v[182:185], v[36:39]
	v_mfma_f32_16x16x32_bf16 v[32:35], v[242:245], v[182:185], v[32:35]
	v_mfma_f32_16x16x32_bf16 v[20:23], v[234:237], v[218:221], v[20:23]
	v_mfma_f32_16x16x32_bf16 v[16:19], v[242:245], v[218:221], v[16:19]
	v_mfma_f32_16x16x32_bf16 v[4:7], v[234:237], v[226:229], v[4:7]
	v_mfma_f32_16x16x32_bf16 v[0:3], v[242:245], v[226:229], v[0:3]
	s_add_i32 s29, 0, 0x18000
	s_barrier
	s_add_u32 s10, s10, 0x40000
	s_addc_u32 s11, s11, 0
	s_mov_b32 m0, s36
	ds_read_b128 v[170:173], v216 offset:32768
	ds_read_b128 v[178:181], v216 offset:34816
	ds_read_b128 v[186:189], v216 offset:36864
	ds_read_b128 v[222:225], v216 offset:38912
	ds_read_b128 v[174:177], v216 offset:33792
	ds_read_b128 v[182:185], v216 offset:35840
	ds_read_b128 v[218:221], v216 offset:37888
	ds_read_b128 v[226:229], v216 offset:39936
	global_load_lds_dwordx4 v150, s[10:11]
	s_mov_b32 m0, s37
	s_nop 0
	global_load_lds_dwordx4 v152, s[10:11]
	s_waitcnt lgkmcnt(8)
	s_waitcnt vmcnt(10)
	s_barrier
	s_waitcnt lgkmcnt(4)
	v_mfma_f32_16x16x32_bf16 v[124:127], v[128:131], v[170:173], v[124:127]
	v_mfma_f32_16x16x32_bf16 v[120:123], v[162:165], v[170:173], v[120:123]
	v_mfma_f32_16x16x32_bf16 v[108:111], v[128:131], v[178:181], v[108:111]
	v_mfma_f32_16x16x32_bf16 v[104:107], v[162:165], v[178:181], v[104:107]
	v_mfma_f32_16x16x32_bf16 v[92:95], v[128:131], v[186:189], v[92:95]
	v_mfma_f32_16x16x32_bf16 v[88:91], v[162:165], v[186:189], v[88:91]
	v_mfma_f32_16x16x32_bf16 v[76:79], v[128:131], v[222:225], v[76:79]
	v_mfma_f32_16x16x32_bf16 v[72:75], v[162:165], v[222:225], v[72:75]
	s_waitcnt lgkmcnt(0)
	v_mfma_f32_16x16x32_bf16 v[124:127], v[158:161], v[174:177], v[124:127]
	v_mfma_f32_16x16x32_bf16 v[120:123], v[166:169], v[174:177], v[120:123]
	v_mfma_f32_16x16x32_bf16 v[108:111], v[158:161], v[182:185], v[108:111]
	v_mfma_f32_16x16x32_bf16 v[104:107], v[166:169], v[182:185], v[104:107]
	v_mfma_f32_16x16x32_bf16 v[92:95], v[158:161], v[218:221], v[92:95]
	v_mfma_f32_16x16x32_bf16 v[88:91], v[166:169], v[218:221], v[88:91]
	v_mfma_f32_16x16x32_bf16 v[76:79], v[158:161], v[226:229], v[76:79]
	v_mfma_f32_16x16x32_bf16 v[72:75], v[166:169], v[226:229], v[72:75]
	s_barrier
	s_add_i32 s10, 0, 0x1c000
	s_add_i32 s11, s29, s15
	s_mov_b32 m0, s11
	ds_read_b128 v[230:233], v202
	ds_read_b128 v[238:241], v202 offset:2048
	ds_read_b128 v[234:237], v202 offset:1024
	ds_read_b128 v[242:245], v202 offset:3072
	s_add_u32 s98, s6, 0x80
	s_addc_u32 s99, s7, 0
	global_load_lds_dwordx4 v150, s[98:99]
	s_add_i32 m0, s11, 0x2000
	s_nop 0
	global_load_lds_dwordx4 v152, s[98:99]
	s_waitcnt vmcnt(10)
	s_barrier
	s_waitcnt lgkmcnt(2)
	v_mfma_f32_16x16x32_bf16 v[116:119], v[230:233], v[170:173], v[116:119]
	v_mfma_f32_16x16x32_bf16 v[112:115], v[238:241], v[170:173], v[112:115]
	v_mfma_f32_16x16x32_bf16 v[100:103], v[230:233], v[178:181], v[100:103]
	v_mfma_f32_16x16x32_bf16 v[96:99], v[238:241], v[178:181], v[96:99]
	v_mfma_f32_16x16x32_bf16 v[84:87], v[230:233], v[186:189], v[84:87]
	v_mfma_f32_16x16x32_bf16 v[80:83], v[238:241], v[186:189], v[80:83]
	v_mfma_f32_16x16x32_bf16 v[68:71], v[230:233], v[222:225], v[68:71]
	v_mfma_f32_16x16x32_bf16 v[64:67], v[238:241], v[222:225], v[64:67]
	s_waitcnt lgkmcnt(0)
	v_mfma_f32_16x16x32_bf16 v[116:119], v[234:237], v[174:177], v[116:119]
	v_mfma_f32_16x16x32_bf16 v[112:115], v[242:245], v[174:177], v[112:115]
	v_mfma_f32_16x16x32_bf16 v[100:103], v[234:237], v[182:185], v[100:103]
	v_mfma_f32_16x16x32_bf16 v[96:99], v[242:245], v[182:185], v[96:99]
	v_mfma_f32_16x16x32_bf16 v[84:87], v[234:237], v[218:221], v[84:87]
	v_mfma_f32_16x16x32_bf16 v[80:83], v[242:245], v[218:221], v[80:83]
	v_mfma_f32_16x16x32_bf16 v[68:71], v[234:237], v[226:229], v[68:71]
	v_mfma_f32_16x16x32_bf16 v[64:67], v[242:245], v[226:229], v[64:67]
	s_mov_b32 m0, s52
	v_lshl_add_u64 v[190:191], v[248:249], 0, s[66:67]
	s_barrier
	ds_read_b128 v[170:173], v216 offset:49152
	ds_read_b128 v[178:181], v216 offset:51200
	ds_read_b128 v[186:189], v216 offset:53248
	ds_read_b128 v[222:225], v216 offset:55296
	ds_read_b128 v[174:177], v216 offset:50176
	ds_read_b128 v[182:185], v216 offset:52224
	ds_read_b128 v[218:221], v216 offset:54272
	ds_read_b128 v[226:229], v216 offset:56320
	global_load_lds_dwordx4 v[190:191], off
	v_lshl_add_u64 v[190:191], v[250:251], 0, s[66:67]
	s_mov_b32 m0, s53
	s_nop 0
	global_load_lds_dwordx4 v[190:191], off
	s_waitcnt vmcnt(10)
	s_barrier
	s_waitcnt lgkmcnt(4)
	v_mfma_f32_16x16x32_bf16 v[60:63], v[128:131], v[170:173], v[60:63]
	v_mfma_f32_16x16x32_bf16 v[56:59], v[162:165], v[170:173], v[56:59]
	v_mfma_f32_16x16x32_bf16 v[44:47], v[128:131], v[178:181], v[44:47]
	v_mfma_f32_16x16x32_bf16 v[40:43], v[162:165], v[178:181], v[40:43]
	v_mfma_f32_16x16x32_bf16 v[28:31], v[128:131], v[186:189], v[28:31]
	v_mfma_f32_16x16x32_bf16 v[24:27], v[162:165], v[186:189], v[24:27]
	v_mfma_f32_16x16x32_bf16 v[12:15], v[128:131], v[222:225], v[12:15]
	v_mfma_f32_16x16x32_bf16 v[8:11], v[162:165], v[222:225], v[8:11]
	s_waitcnt lgkmcnt(0)
	v_mfma_f32_16x16x32_bf16 v[60:63], v[158:161], v[174:177], v[60:63]
	v_mfma_f32_16x16x32_bf16 v[56:59], v[166:169], v[174:177], v[56:59]
	v_mfma_f32_16x16x32_bf16 v[44:47], v[158:161], v[182:185], v[44:47]
	v_mfma_f32_16x16x32_bf16 v[40:43], v[166:169], v[182:185], v[40:43]
	v_mfma_f32_16x16x32_bf16 v[28:31], v[158:161], v[218:221], v[28:31]
	v_mfma_f32_16x16x32_bf16 v[24:27], v[166:169], v[218:221], v[24:27]
	v_mfma_f32_16x16x32_bf16 v[12:15], v[158:161], v[226:229], v[12:15]
	v_mfma_f32_16x16x32_bf16 v[8:11], v[166:169], v[226:229], v[8:11]
	s_barrier
	s_add_u32 s6, s6, 0x40080
	s_addc_u32 s7, s7, 0
	s_add_i32 s10, s10, s15
	s_mov_b32 m0, s10
	s_nop 0
	global_load_lds_dwordx4 v150, s[6:7]
	s_add_i32 m0, s10, 0x2000
	s_nop 0
	global_load_lds_dwordx4 v152, s[6:7]
	ds_read_b128 v[128:131], v246
	ds_read_b128 v[158:161], v246 offset:1024
	ds_read_b128 v[162:165], v246 offset:2048
	ds_read_b128 v[166:169], v246 offset:3072
	s_waitcnt vmcnt(10)
	s_barrier
	v_mfma_f32_16x16x32_bf16 v[52:55], v[230:233], v[170:173], v[52:55]
	v_mfma_f32_16x16x32_bf16 v[48:51], v[238:241], v[170:173], v[48:51]
	v_mfma_f32_16x16x32_bf16 v[36:39], v[230:233], v[178:181], v[36:39]
	v_mfma_f32_16x16x32_bf16 v[32:35], v[238:241], v[178:181], v[32:35]
	v_mfma_f32_16x16x32_bf16 v[20:23], v[230:233], v[186:189], v[20:23]
	v_mfma_f32_16x16x32_bf16 v[16:19], v[238:241], v[186:189], v[16:19]
	v_mfma_f32_16x16x32_bf16 v[4:7], v[230:233], v[222:225], v[4:7]
	v_mfma_f32_16x16x32_bf16 v[0:3], v[238:241], v[222:225], v[0:3]
	v_mfma_f32_16x16x32_bf16 v[52:55], v[234:237], v[174:177], v[52:55]
	v_mfma_f32_16x16x32_bf16 v[48:51], v[242:245], v[174:177], v[48:51]
	v_mfma_f32_16x16x32_bf16 v[36:39], v[234:237], v[182:185], v[36:39]
	v_mfma_f32_16x16x32_bf16 v[32:35], v[242:245], v[182:185], v[32:35]
	v_mfma_f32_16x16x32_bf16 v[20:23], v[234:237], v[218:221], v[20:23]
	v_mfma_f32_16x16x32_bf16 v[16:19], v[242:245], v[218:221], v[16:19]
	v_mfma_f32_16x16x32_bf16 v[4:7], v[234:237], v[226:229], v[4:7]
	v_mfma_f32_16x16x32_bf16 v[0:3], v[242:245], v[226:229], v[0:3]
	s_add_i32 s28, s28, 2
	s_add_u32 s2, s2, 0x100
	s_addc_u32 s3, s3, 0
	s_add_u32 s19, s19, 0x100
	s_addc_u32 s27, s27, 0
	s_cmp_gt_u32 s28, 13
	s_barrier
	s_cbranch_scc0 .LBB0_145
	s_waitcnt lgkmcnt(0)
	v_mov_b32_e32 v166, v135
	s_mov_b64 s[2:3], s[0:1]
	v_readfirstlane_b32 s27, v166
	s_bfe_u32 s19, s27, 0x20006
	s_load_dwordx2 s[30:31], s[2:3], 0x88
	s_mov_b64 s[2:3], s[0:1]
	s_cmp_gt_i32 s8, 31
	s_load_dwordx2 s[28:29], s[2:3], 0x80
	s_cselect_b64 s[6:7], -1, 0
	s_cmp_lt_i32 s8, 32
	s_cselect_b64 s[2:3], -1, 0
	s_ashr_i32 s9, s27, 2
	s_lshl_b32 s8, s8, 8
	s_and_b32 s17, s9, 0xffffffc0
	v_and_b32_e32 v217, 15, v166
	s_add_i32 s17, s17, s8
	v_bfe_u32 v186, v166, 4, 2
	v_or_b32_e32 v158, s17, v217
	s_cmp_gt_i32 s26, 3
	s_mov_b64 s[8:9], -1
	s_cbranch_scc0 .LBB0_829
	s_cmp_gt_u32 s26, 5
	s_cbranch_scc0 .LBB0_409
	s_cmp_gt_u32 s26, 8
	s_cbranch_scc0 .LBB0_406
	s_waitcnt lgkmcnt(0)
	v_and_b32_e32 v128, 1, v166
	v_cmp_eq_u32_e64 s[8:9], 0, v128
	v_cmp_eq_u32_e32 vcc, 1, v128
	s_mov_b32 s10, 0x05040100
	s_mov_b32 s11, 0x07060302
	s_cmp_eq_u32 s6, 0
	s_cbranch_scc1 .Lvf_f_c
